# cache policy: nt on P5's once-read x loads (keep the P4-written fp16 rows in the memory-side cache)
# speedup vs baseline: 1.0046x; 1.0046x over previous
; #define GAS __attribute__((address_space(1)))
; __device__ __forceinline__ float h_lo(unsigned w) { return (float)__builtin_bit_cast(_Float16, (unsigned short)(w & 0xffffu)); }
; __device__ __forceinline__ float h_hi(unsigned w) { return (float)__builtin_bit_cast(_Float16, (unsigned short)(w >> 16)); }
; template <bool SAMPLE, bool PRE = false> __device__ __forceinline__ void p5_row(Frame& F, int m, float* dst, const f32x4* xpre = nullptr) {
;     f32x4 v[16];
;     const GAS f32x4* x8 = (const GAS f32x4*)((SAMPLE ? F.in[2] + (size_t)(m - MP) * DM : F.in[0] + (size_t)m * DM)) + 2 * F.lane;
;     if (!SAMPLE) {
;         const GAS u32x4* yr = (const GAS u32x4*)(F.ws + WS_YH + (size_t)m * DM * 2) + F.lane;
;         u32x4 w[8];
; #pragma unroll
;         for (int j = 0; j < 8; ++j) { w[j] = yr[64 * j]; if constexpr (PRE) { v[2 * j] = xpre[2 * j]; v[2 * j + 1] = xpre[2 * j + 1]; } else { v[2 * j] = x8[128 * j]; v[2 * j + 1] = x8[128 * j + 1]; } }
; #pragma unroll
;         for (int j = 0; j < 8; ++j) { v[2 * j] += (f32x4){h_lo(w[j].x), h_hi(w[j].x), h_lo(w[j].y), h_hi(w[j].y)}; v[2 * j + 1] += (f32x4){h_lo(w[j].z), h_hi(w[j].z), h_lo(w[j].w), h_hi(w[j].w)}; }
.LBB0_842:
	v_lshl_add_u64 v[96:97], s[8:9], 0, v[130:131]
	global_load_dwordx4 v[12:15], v[94:95], off
	global_load_dwordx4 v[8:11], v[94:95], off offset:1024
	global_load_dwordx4 v[0:3], v[94:95], off offset:2048
	global_load_dwordx4 v[4:7], v[94:95], off offset:3072
	v_add_co_u32_e32 v136, vcc, 0x1000, v96
	v_lshl_add_u64 v[132:133], v[96:97], 0, s[4:5]
	s_nop 0
	v_addc_co_u32_e32 v137, vcc, 0, v97, vcc
	v_add_co_u32_e32 v156, vcc, 0x1000, v94
	v_lshl_add_u64 v[140:141], v[96:97], 0, s[12:13]
	s_nop 0
	v_addc_co_u32_e32 v157, vcc, 0, v95, vcc
	global_load_dwordx4 v[68:71], v[80:81], off offset:16
	global_load_dwordx4 v[76:79], v[80:81], off
	global_load_dwordx4 v[60:63], v[80:81], off offset:2064
	global_load_dwordx4 v[72:75], v[80:81], off offset:2048
	global_load_dwordx4 v[52:55], v[82:83], off offset:16
	global_load_dwordx4 v[64:67], v[82:83], off
	global_load_dwordx4 v[44:47], v[84:85], off offset:16
	global_load_dwordx4 v[56:59], v[84:85], off
	global_load_dwordx4 v[36:39], v[86:87], off offset:16
	global_load_dwordx4 v[48:51], v[86:87], off
	global_load_dwordx4 v[28:31], v[88:89], off offset:16
	global_load_dwordx4 v[40:43], v[88:89], off
	global_load_dwordx4 v[20:23], v[90:91], off offset:16
	global_load_dwordx4 v[32:35], v[90:91], off
	global_load_dwordx4 v[16:19], v[92:93], off offset:16
	global_load_dwordx4 v[24:27], v[92:93], off
	global_load_dwordx4 v[110:113], v[96:97], off offset:16 nt
	global_load_dwordx4 v[114:117], v[96:97], off nt
	global_load_dwordx4 v[118:121], v[96:97], off offset:2064 nt
	global_load_dwordx4 v[122:125], v[96:97], off offset:2048 nt
	global_load_dwordx4 v[126:129], v[136:137], off nt
	s_nop 0
	global_load_dwordx4 v[132:135], v[132:133], off offset:16 nt
	s_nop 0
	global_load_dwordx4 v[136:139], v[136:137], off offset:2048 nt
	s_nop 0
	global_load_dwordx4 v[140:143], v[140:141], off offset:16 nt
	s_nop 0
	global_load_dwordx4 v[144:147], v[156:157], off
	global_load_dwordx4 v[148:151], v[156:157], off offset:1024
	global_load_dwordx4 v[152:155], v[156:157], off offset:2048
	v_add_co_u32_e32 v168, vcc, 0x2000, v96
	global_load_dwordx4 v[156:159], v[156:157], off offset:3072
	v_lshl_add_u64 v[164:165], v[96:97], 0, s[14:15]
	v_lshl_add_u64 v[172:173], v[96:97], 0, s[16:17]
	v_addc_co_u32_e32 v169, vcc, 0, v97, vcc
	global_load_dwordx4 v[160:163], v[168:169], off nt
	s_nop 0
	global_load_dwordx4 v[164:167], v[164:165], off offset:16 nt
	s_nop 0
	global_load_dwordx4 v[168:171], v[168:169], off offset:2048 nt
	s_nop 0
	global_load_dwordx4 v[172:175], v[172:173], off offset:16 nt
	v_lshl_add_u64 v[180:181], v[96:97], 0, s[18:19]
	v_lshl_add_u64 v[188:189], v[96:97], 0, s[20:21]
	v_add_co_u32_e32 v96, vcc, 0x3000, v96
	v_lshl_add_u64 v[98:99], s[6:7], 0, v[130:131]
	s_nop 0
	v_addc_co_u32_e32 v97, vcc, 0, v97, vcc
	global_load_dwordx4 v[176:179], v[96:97], off nt
	s_nop 0
	global_load_dwordx4 v[180:183], v[180:181], off offset:16 nt
	s_nop 0
	global_load_dwordx4 v[184:187], v[96:97], off offset:2048 nt
	s_nop 0
	global_load_dwordx4 v[188:191], v[188:189], off offset:16 nt
	v_add_co_u32_e64 v104, s[0:1], s23, v98
	v_mov_b32_e32 v109, 0
	s_nop 0
	v_addc_co_u32_e64 v105, s[0:1], 0, v99, s[0:1]
	v_add_co_u32_e64 v102, s[0:1], s24, v98
	v_mov_b32_e32 v208, 0
	s_nop 0
	v_addc_co_u32_e64 v103, s[0:1], 0, v99, s[0:1]
	v_add_co_u32_e64 v100, s[0:1], s25, v98
	s_add_i32 s22, s22, s28
	s_nop 0
	v_addc_co_u32_e64 v101, s[0:1], 0, v99, s[0:1]
	s_add_u32 s6, s6, s10
	s_addc_u32 s7, s7, s11
	s_add_u32 s8, s8, s10
	s_addc_u32 s9, s9, s11
	v_lshl_add_u64 v[94:95], v[94:95], 0, s[2:3]
	s_cmp_lt_i32 s22, s99
	s_waitcnt vmcnt(39)
	v_cvt_f32_f16_sdwa v97, v12 dst_sel:DWORD dst_unused:UNUSED_PAD src0_sel:WORD_1
	v_cvt_f32_f16_e32 v96, v12
	v_cvt_f32_f16_sdwa v193, v13 dst_sel:DWORD dst_unused:UNUSED_PAD src0_sel:WORD_1
	v_cvt_f32_f16_e32 v192, v13
	v_cvt_f32_f16_sdwa v13, v14 dst_sel:DWORD dst_unused:UNUSED_PAD src0_sel:WORD_1
	v_cvt_f32_f16_e32 v12, v14
	v_cvt_f32_f16_sdwa v195, v15 dst_sel:DWORD dst_unused:UNUSED_PAD src0_sel:WORD_1
	v_cvt_f32_f16_e32 v194, v15
	s_waitcnt vmcnt(38)
	v_cvt_f32_f16_sdwa v15, v8 dst_sel:DWORD dst_unused:UNUSED_PAD src0_sel:WORD_1
	v_cvt_f32_f16_e32 v14, v8
	v_cvt_f32_f16_sdwa v197, v9 dst_sel:DWORD dst_unused:UNUSED_PAD src0_sel:WORD_1
	v_cvt_f32_f16_e32 v196, v9
	v_cvt_f32_f16_sdwa v9, v10 dst_sel:DWORD dst_unused:UNUSED_PAD src0_sel:WORD_1
	v_cvt_f32_f16_e32 v8, v10
	v_cvt_f32_f16_sdwa v199, v11 dst_sel:DWORD dst_unused:UNUSED_PAD src0_sel:WORD_1
	v_cvt_f32_f16_e32 v198, v11
	s_waitcnt vmcnt(37)
	v_cvt_f32_f16_sdwa v11, v0 dst_sel:DWORD dst_unused:UNUSED_PAD src0_sel:WORD_1
	v_cvt_f32_f16_e32 v10, v0
	v_cvt_f32_f16_sdwa v201, v1 dst_sel:DWORD dst_unused:UNUSED_PAD src0_sel:WORD_1
	v_cvt_f32_f16_e32 v200, v1
	v_cvt_f32_f16_sdwa v1, v2 dst_sel:DWORD dst_unused:UNUSED_PAD src0_sel:WORD_1
	v_cvt_f32_f16_e32 v0, v2
	v_cvt_f32_f16_sdwa v203, v3 dst_sel:DWORD dst_unused:UNUSED_PAD src0_sel:WORD_1
	v_cvt_f32_f16_e32 v202, v3
	s_waitcnt vmcnt(36)
	v_cvt_f32_f16_sdwa v3, v4 dst_sel:DWORD dst_unused:UNUSED_PAD src0_sel:WORD_1
	v_cvt_f32_f16_e32 v2, v4
	v_cvt_f32_f16_sdwa v205, v5 dst_sel:DWORD dst_unused:UNUSED_PAD src0_sel:WORD_1
	v_cvt_f32_f16_e32 v204, v5
	v_cvt_f32_f16_sdwa v5, v6 dst_sel:DWORD dst_unused:UNUSED_PAD src0_sel:WORD_1
	v_cvt_f32_f16_e32 v4, v6
	v_cvt_f32_f16_sdwa v207, v7 dst_sel:DWORD dst_unused:UNUSED_PAD src0_sel:WORD_1
	v_cvt_f32_f16_e32 v206, v7
	s_waitcnt vmcnt(18)
	v_pk_add_f32 v[6:7], v[116:117], v[192:193]
	v_pk_add_f32 v[96:97], v[114:115], v[96:97]
	v_pk_add_f32 v[112:113], v[112:113], v[194:195]
	v_pk_add_f32 v[12:13], v[110:111], v[12:13]
	s_waitcnt vmcnt(16)
; #define GAS __attribute__((address_space(1)))
; __device__ __forceinline__ float h_lo(unsigned w) { return (float)__builtin_bit_cast(_Float16, (unsigned short)(w & 0xffffu)); }
; __device__ __forceinline__ float h_hi(unsigned w) { return (float)__builtin_bit_cast(_Float16, (unsigned short)(w >> 16)); }
; template <bool SAMPLE, bool PRE = false> __device__ __forceinline__ void p5_row(Frame& F, int m, float* dst, const f32x4* xpre = nullptr) {
;     ...
;         for (int j = 0; j < 8; ++j) { w[j] = yr[64 * j]; if constexpr (PRE) { v[2 * j] = xpre[2 * j]; v[2 * j + 1] = xpre[2 * j + 1]; } else { v[2 * j] = x8[128 * j]; v[2 * j + 1] = x8[128 * j + 1]; } }
; #pragma unroll
;         for (int j = 0; j < 8; ++j) { v[2 * j] += (f32x4){h_lo(w[j].x), h_hi(w[j].x), h_lo(w[j].y), h_hi(w[j].y)}; v[2 * j + 1] += (f32x4){h_lo(w[j].z), h_hi(w[j].z), h_lo(w[j].w), h_hi(w[j].w)}; }
;     } else {
; #pragma unroll
;         for (int j = 0; j < 8; ++j) { v[2 * j] = x8[128 * j]; v[2 * j + 1] = x8[128 * j + 1]; }
; #pragma unroll 2
;         for (int p = 0; p < 8; ++p) { const GAS u32x4* pr = (const GAS u32x4*)(F.ws + WS_SLAB + ((size_t)p * MS + (m - MP)) * DM * 2) + F.lane;
;             u32x4 w[8];
; #pragma unroll
;             for (int j = 0; j < 8; ++j) w[j] = pr[64 * j];
; #pragma unroll
;             for (int j = 0; j < 8; ++j) { v[2 * j] += (f32x4){h_lo(w[j].x), h_hi(w[j].x), h_lo(w[j].y), h_hi(w[j].y)}; v[2 * j + 1] += (f32x4){h_lo(w[j].z), h_hi(w[j].z), h_lo(w[j].w), h_hi(w[j].w)}; } }
;     }
;     float s = 0.f;
; #pragma unroll
;     for (int j = 0; j < 16; ++j) s += (v[j].x * v[j].x + v[j].y * v[j].y) + (v[j].z * v[j].z + v[j].w * v[j].w);
	v_pk_add_f32 v[110:111], v[124:125], v[196:197]
	v_pk_add_f32 v[14:15], v[122:123], v[14:15]
	v_pk_add_f32 v[114:115], v[120:121], v[198:199]
	v_pk_add_f32 v[8:9], v[118:119], v[8:9]
	s_waitcnt vmcnt(15)
	v_pk_add_f32 v[116:117], v[128:129], v[200:201]
	v_pk_add_f32 v[10:11], v[126:127], v[10:11]
	s_waitcnt vmcnt(14)
	v_pk_add_f32 v[118:119], v[134:135], v[202:203]
	v_pk_add_f32 v[0:1], v[132:133], v[0:1]
	s_waitcnt vmcnt(13)
	v_pk_add_f32 v[120:121], v[138:139], v[204:205]
	v_pk_add_f32 v[2:3], v[136:137], v[2:3]
	s_waitcnt vmcnt(12)
	v_pk_add_f32 v[122:123], v[142:143], v[206:207]
	v_pk_add_f32 v[4:5], v[140:141], v[4:5]
	s_waitcnt vmcnt(11)
	v_cvt_f32_f16_e32 v124, v144
	v_cvt_f32_f16_sdwa v125, v144 dst_sel:DWORD dst_unused:UNUSED_PAD src0_sel:WORD_1
	v_cvt_f32_f16_e32 v126, v145
	v_cvt_f32_f16_sdwa v127, v145 dst_sel:DWORD dst_unused:UNUSED_PAD src0_sel:WORD_1
	v_cvt_f32_f16_e32 v128, v146
	v_cvt_f32_f16_sdwa v129, v146 dst_sel:DWORD dst_unused:UNUSED_PAD src0_sel:WORD_1
	v_cvt_f32_f16_e32 v132, v147
	v_cvt_f32_f16_sdwa v133, v147 dst_sel:DWORD dst_unused:UNUSED_PAD src0_sel:WORD_1
	s_waitcnt vmcnt(10)
	v_cvt_f32_f16_e32 v134, v148
	v_cvt_f32_f16_sdwa v135, v148 dst_sel:DWORD dst_unused:UNUSED_PAD src0_sel:WORD_1
	v_cvt_f32_f16_e32 v136, v149
	v_cvt_f32_f16_sdwa v137, v149 dst_sel:DWORD dst_unused:UNUSED_PAD src0_sel:WORD_1
	v_cvt_f32_f16_e32 v138, v150
	v_cvt_f32_f16_sdwa v139, v150 dst_sel:DWORD dst_unused:UNUSED_PAD src0_sel:WORD_1
	v_cvt_f32_f16_e32 v140, v151
	v_cvt_f32_f16_sdwa v141, v151 dst_sel:DWORD dst_unused:UNUSED_PAD src0_sel:WORD_1
	s_waitcnt vmcnt(9)
	v_cvt_f32_f16_e32 v142, v152
	v_cvt_f32_f16_sdwa v143, v152 dst_sel:DWORD dst_unused:UNUSED_PAD src0_sel:WORD_1
	v_cvt_f32_f16_e32 v144, v153
	v_cvt_f32_f16_sdwa v145, v153 dst_sel:DWORD dst_unused:UNUSED_PAD src0_sel:WORD_1
	v_cvt_f32_f16_e32 v146, v154
	v_cvt_f32_f16_sdwa v147, v154 dst_sel:DWORD dst_unused:UNUSED_PAD src0_sel:WORD_1
	v_cvt_f32_f16_e32 v148, v155
	v_cvt_f32_f16_sdwa v149, v155 dst_sel:DWORD dst_unused:UNUSED_PAD src0_sel:WORD_1
	s_waitcnt vmcnt(8)
	v_cvt_f32_f16_e32 v150, v156
	v_cvt_f32_f16_sdwa v151, v156 dst_sel:DWORD dst_unused:UNUSED_PAD src0_sel:WORD_1
	v_cvt_f32_f16_e32 v152, v157
	v_cvt_f32_f16_sdwa v153, v157 dst_sel:DWORD dst_unused:UNUSED_PAD src0_sel:WORD_1
	v_cvt_f32_f16_e32 v154, v158
	v_cvt_f32_f16_sdwa v155, v158 dst_sel:DWORD dst_unused:UNUSED_PAD src0_sel:WORD_1
	v_cvt_f32_f16_e32 v156, v159
	v_cvt_f32_f16_sdwa v157, v159 dst_sel:DWORD dst_unused:UNUSED_PAD src0_sel:WORD_1
	v_mul_f32_e32 v158, v97, v97
	v_mul_f32_e32 v159, v7, v7
	v_mul_f32_e32 v192, v13, v13
	v_mul_f32_e32 v193, v113, v113
	v_mul_f32_e32 v194, v15, v15
	v_mul_f32_e32 v195, v111, v111
	v_fmac_f32_e32 v158, v96, v96
	v_fmac_f32_e32 v159, v6, v6
	v_fmac_f32_e32 v192, v12, v12
	v_fmac_f32_e32 v193, v112, v112
	v_mul_f32_e32 v196, v9, v9
	v_mul_f32_e32 v197, v115, v115
	v_fmac_f32_e32 v194, v14, v14
	v_fmac_f32_e32 v195, v110, v110
	v_add_f32_e32 v158, v158, v159
	v_add_f32_e32 v159, v192, v193
	v_mul_f32_e32 v198, v11, v11
	v_mul_f32_e32 v199, v117, v117
	v_fmac_f32_e32 v196, v8, v8
	v_fmac_f32_e32 v197, v114, v114
	v_add_f32_e32 v192, v194, v195
	v_add_f32_e32 v158, v158, v159
	v_mul_f32_e32 v200, v1, v1
	v_mul_f32_e32 v201, v119, v119
	v_fmac_f32_e32 v198, v10, v10
	v_fmac_f32_e32 v199, v116, v116
	v_add_f32_e32 v193, v196, v197
	v_add_f32_e32 v158, v158, v192
	v_mul_f32_e32 v202, v3, v3
	v_mul_f32_e32 v203, v121, v121
	v_fmac_f32_e32 v200, v0, v0
	v_fmac_f32_e32 v201, v118, v118
	v_add_f32_e32 v194, v198, v199
	v_add_f32_e32 v158, v193, v158
	v_mul_f32_e32 v204, v5, v5
	v_mul_f32_e32 v205, v123, v123
	v_fmac_f32_e32 v202, v2, v2
	v_fmac_f32_e32 v203, v120, v120
	v_add_f32_e32 v195, v200, v201
	s_waitcnt vmcnt(7)
	v_pk_add_f32 v[126:127], v[162:163], v[126:127]
	v_pk_add_f32 v[124:125], v[160:161], v[124:125]
	v_add_f32_e32 v158, v158, v194
	v_fmac_f32_e32 v204, v4, v4
	v_fmac_f32_e32 v205, v122, v122
	v_add_f32_e32 v196, v202, v203
	s_waitcnt vmcnt(6)
	v_pk_add_f32 v[132:133], v[166:167], v[132:133]
	v_pk_add_f32 v[128:129], v[164:165], v[128:129]
	v_mul_f32_e32 v159, v125, v125
	v_mul_f32_e32 v160, v127, v127
	v_add_f32_e32 v158, v195, v158
	v_add_f32_e32 v197, v204, v205
	s_waitcnt vmcnt(5)
	v_pk_add_f32 v[136:137], v[170:171], v[136:137]
	v_pk_add_f32 v[134:135], v[168:169], v[134:135]
	v_mul_f32_e32 v161, v129, v129
	v_mul_f32_e32 v162, v133, v133
	v_fmac_f32_e32 v159, v124, v124
	v_fmac_f32_e32 v160, v126, v126
	v_add_f32_e32 v158, v158, v196
	s_waitcnt vmcnt(4)
	v_pk_add_f32 v[140:141], v[174:175], v[140:141]
	v_pk_add_f32 v[138:139], v[172:173], v[138:139]
	v_mul_f32_e32 v163, v135, v135
	v_mul_f32_e32 v164, v137, v137
	v_fmac_f32_e32 v161, v128, v128
	v_fmac_f32_e32 v162, v132, v132
	v_add_f32_e32 v159, v159, v160
	v_add_f32_e32 v158, v197, v158
	s_waitcnt vmcnt(3)
	v_pk_add_f32 v[144:145], v[178:179], v[144:145]
	v_pk_add_f32 v[142:143], v[176:177], v[142:143]
	v_mul_f32_e32 v165, v139, v139
	v_mul_f32_e32 v166, v141, v141
	v_fmac_f32_e32 v163, v134, v134
	v_fmac_f32_e32 v164, v136, v136
	v_add_f32_e32 v160, v161, v162
	v_add_f32_e32 v158, v158, v159
	s_waitcnt vmcnt(2)
	v_pk_add_f32 v[148:149], v[182:183], v[148:149]
	v_pk_add_f32 v[146:147], v[180:181], v[146:147]
	v_mul_f32_e32 v167, v143, v143
	v_mul_f32_e32 v168, v145, v145
	v_fmac_f32_e32 v165, v138, v138
	v_fmac_f32_e32 v166, v140, v140
	v_add_f32_e32 v161, v163, v164
	v_add_f32_e32 v158, v160, v158
	s_waitcnt vmcnt(1)
	v_pk_add_f32 v[152:153], v[186:187], v[152:153]
	v_pk_add_f32 v[150:151], v[184:185], v[150:151]
	v_mul_f32_e32 v169, v147, v147
	v_mul_f32_e32 v170, v149, v149
	v_fmac_f32_e32 v167, v142, v142
	v_fmac_f32_e32 v168, v144, v144
	v_add_f32_e32 v162, v165, v166
	v_add_f32_e32 v158, v158, v161
	s_waitcnt vmcnt(0)
; #define GAS __attribute__((address_space(1)))
; template <bool SAMPLE, bool PRE = false> __device__ __forceinline__ void p5_row(Frame& F, int m, float* dst, const f32x4* xpre = nullptr) {
;     ...
;     float s = 0.f;
; #pragma unroll
;     for (int j = 0; j < 16; ++j) s += (v[j].x * v[j].x + v[j].y * v[j].y) + (v[j].z * v[j].z + v[j].w * v[j].w);
;     const float rstd = 1.0f / sqrtf(wave_sum(s) * (1.0f / DM) + EPS);
;     const GAS f32x4* g8 = (const GAS f32x4*)F.in[20] + 2 * F.lane; GAS f32x4* y8 = (GAS f32x4*)(dst + (size_t)m * DM) + 2 * F.lane;
;     f32x4 gv[16];
; #pragma unroll
;     for (int j = 0; j < 8; ++j) { gv[2 * j] = g8[128 * j]; gv[2 * j + 1] = g8[128 * j + 1]; }
; #pragma unroll
;     for (int j = 0; j < 8; ++j) { y8[128 * j] = v[2 * j] * rstd * gv[2 * j]; y8[128 * j + 1] = v[2 * j + 1] * rstd * gv[2 * j + 1]; }
	v_pk_add_f32 v[156:157], v[190:191], v[156:157]
	v_pk_add_f32 v[154:155], v[188:189], v[154:155]
	v_mul_f32_e32 v171, v151, v151
	v_mul_f32_e32 v172, v153, v153
	v_fmac_f32_e32 v169, v146, v146
	v_fmac_f32_e32 v170, v148, v148
	v_add_f32_e32 v163, v167, v168
	v_add_f32_e32 v158, v162, v158
	v_mul_f32_e32 v173, v155, v155
	v_mul_f32_e32 v174, v157, v157
	v_fmac_f32_e32 v171, v150, v150
	v_fmac_f32_e32 v172, v152, v152
	v_add_f32_e32 v164, v169, v170
	v_add_f32_e32 v158, v158, v163
	v_fmac_f32_e32 v173, v154, v154
	v_fmac_f32_e32 v174, v156, v156
	v_add_f32_e32 v165, v171, v172
	v_add_f32_e32 v158, v164, v158
	v_add_f32_e32 v166, v173, v174
	v_add_f32_e32 v158, v158, v165
	v_add_f32_e32 v158, v166, v158
	s_nop 1
	v_add_f32_dpp v158, v158, v158 quad_perm:[1,0,3,2] row_mask:0xf bank_mask:0xf bound_ctrl:1
	s_nop 1
	v_add_f32_dpp v158, v158, v158 quad_perm:[2,3,0,1] row_mask:0xf bank_mask:0xf bound_ctrl:1
	s_nop 1
	v_add_f32_dpp v158, v158, v158 row_half_mirror row_mask:0xf bank_mask:0xf bound_ctrl:1
	s_nop 1
	v_add_f32_dpp v158, v158, v158 row_mirror row_mask:0xf bank_mask:0xf bound_ctrl:1
	s_nop 1
	v_mov_b32_dpp v109, v158 row_bcast:15 row_mask:0xa bank_mask:0xf
	v_add_f32_e32 v109, v158, v109
	s_nop 1
	v_mov_b32_dpp v208, v109 row_bcast:31 row_mask:0xc bank_mask:0xf
	v_add_f32_e32 v109, v109, v208
	s_nop 0
	v_readlane_b32 s0, v109, 63
	s_nop 1
	v_fma_f32 v109, s0, v107, v106
	v_mul_f32_e32 v158, 0x4f800000, v109
	v_cmp_gt_f32_e32 vcc, s26, v109
	s_nop 1
	v_cndmask_b32_e32 v109, v109, v158, vcc
	v_sqrt_f32_e32 v158, v109
	s_nop 0
	v_add_u32_e32 v159, -1, v158
	v_add_u32_e32 v160, 1, v158
	v_fma_f32 v161, -v159, v158, v109
	v_fma_f32 v162, -v160, v158, v109
	v_cmp_ge_f32_e64 s[0:1], 0, v161
	s_nop 1
	v_cndmask_b32_e64 v158, v158, v159, s[0:1]
	v_cmp_lt_f32_e64 s[0:1], 0, v162
	s_nop 1
	v_cndmask_b32_e64 v158, v158, v160, s[0:1]
	v_mul_f32_e32 v159, 0x37800000, v158
	v_cndmask_b32_e32 v158, v158, v159, vcc
	v_cmp_class_f32_e32 vcc, v109, v108
	s_nop 1
	v_cndmask_b32_e32 v109, v158, v109, vcc
	v_div_scale_f32 v158, s[0:1], v109, v109, 1.0
	v_rcp_f32_e32 v160, v158
	v_div_scale_f32 v159, vcc, 1.0, v109, 1.0
	v_fma_f32 v161, -v158, v160, 1.0
	v_fmac_f32_e32 v160, v161, v160
	v_mul_f32_e32 v161, v159, v160
	v_fma_f32 v162, -v158, v161, v159
	v_fmac_f32_e32 v161, v162, v160
	v_fma_f32 v158, -v158, v161, v159
	v_div_fmas_f32 v158, v158, v160, v161
	v_div_fixup_f32 v158, v158, v109, 1.0
	v_pk_mul_f32 v[96:97], v[96:97], v[158:159] op_sel_hi:[1,0]
	v_pk_mul_f32 v[6:7], v[6:7], v[158:159] op_sel_hi:[1,0]
	v_pk_mul_f32 v[12:13], v[12:13], v[158:159] op_sel_hi:[1,0]
	v_pk_mul_f32 v[112:113], v[112:113], v[158:159] op_sel_hi:[1,0]
	v_pk_mul_f32 v[14:15], v[14:15], v[158:159] op_sel_hi:[1,0]
	v_pk_mul_f32 v[110:111], v[110:111], v[158:159] op_sel_hi:[1,0]
	v_pk_mul_f32 v[160:161], v[8:9], v[158:159] op_sel_hi:[1,0]
	v_pk_mul_f32 v[114:115], v[114:115], v[158:159] op_sel_hi:[1,0]
	v_pk_mul_f32 v[162:163], v[10:11], v[158:159] op_sel_hi:[1,0]
	v_pk_mul_f32 v[116:117], v[116:117], v[158:159] op_sel_hi:[1,0]
	v_pk_mul_f32 v[164:165], v[0:1], v[158:159] op_sel_hi:[1,0]
	v_pk_mul_f32 v[118:119], v[118:119], v[158:159] op_sel_hi:[1,0]
	v_pk_mul_f32 v[166:167], v[2:3], v[158:159] op_sel_hi:[1,0]
	v_pk_mul_f32 v[120:121], v[120:121], v[158:159] op_sel_hi:[1,0]
	v_pk_mul_f32 v[168:169], v[4:5], v[158:159] op_sel_hi:[1,0]
	v_pk_mul_f32 v[122:123], v[122:123], v[158:159] op_sel_hi:[1,0]
	v_pk_mul_f32 v[124:125], v[124:125], v[158:159] op_sel_hi:[1,0]
	v_pk_mul_f32 v[126:127], v[126:127], v[158:159] op_sel_hi:[1,0]
	v_pk_mul_f32 v[128:129], v[128:129], v[158:159] op_sel_hi:[1,0]
	v_pk_mul_f32 v[132:133], v[132:133], v[158:159] op_sel_hi:[1,0]
	v_pk_mul_f32 v[134:135], v[134:135], v[158:159] op_sel_hi:[1,0]
	v_pk_mul_f32 v[136:137], v[136:137], v[158:159] op_sel_hi:[1,0]
	v_pk_mul_f32 v[138:139], v[138:139], v[158:159] op_sel_hi:[1,0]
	v_pk_mul_f32 v[140:141], v[140:141], v[158:159] op_sel_hi:[1,0]
	v_pk_mul_f32 v[142:143], v[142:143], v[158:159] op_sel_hi:[1,0]
	v_pk_mul_f32 v[144:145], v[144:145], v[158:159] op_sel_hi:[1,0]
	v_pk_mul_f32 v[146:147], v[146:147], v[158:159] op_sel_hi:[1,0]
	v_pk_mul_f32 v[148:149], v[148:149], v[158:159] op_sel_hi:[1,0]
	v_pk_mul_f32 v[150:151], v[150:151], v[158:159] op_sel_hi:[1,0]
	v_pk_mul_f32 v[152:153], v[152:153], v[158:159] op_sel_hi:[1,0]
	v_pk_mul_f32 v[154:155], v[154:155], v[158:159] op_sel_hi:[1,0]
	v_pk_mul_f32 v[156:157], v[156:157], v[158:159] op_sel_hi:[1,0]
	v_pk_mul_f32 v[2:3], v[78:79], v[6:7]
	v_pk_mul_f32 v[0:1], v[76:77], v[96:97]
	v_pk_mul_f32 v[6:7], v[70:71], v[112:113]
	v_pk_mul_f32 v[4:5], v[68:69], v[12:13]
	v_pk_mul_f32 v[10:11], v[74:75], v[110:111]
	v_pk_mul_f32 v[8:9], v[72:73], v[14:15]
	v_pk_mul_f32 v[14:15], v[62:63], v[114:115]
	v_pk_mul_f32 v[12:13], v[60:61], v[160:161]
	v_pk_mul_f32 v[62:63], v[66:67], v[116:117]
	v_pk_mul_f32 v[60:61], v[64:65], v[162:163]
	v_pk_mul_f32 v[54:55], v[54:55], v[118:119]
	v_pk_mul_f32 v[52:53], v[52:53], v[164:165]
	v_pk_mul_f32 v[58:59], v[120:121], v[58:59]
	v_pk_mul_f32 v[56:57], v[166:167], v[56:57]
	v_pk_mul_f32 v[46:47], v[122:123], v[46:47]
	v_pk_mul_f32 v[44:45], v[168:169], v[44:45]
	v_pk_mul_f32 v[50:51], v[126:127], v[50:51]
	v_pk_mul_f32 v[48:49], v[124:125], v[48:49]
	v_pk_mul_f32 v[38:39], v[132:133], v[38:39]
	v_pk_mul_f32 v[36:37], v[128:129], v[36:37]
	v_pk_mul_f32 v[42:43], v[136:137], v[42:43]
	v_pk_mul_f32 v[40:41], v[134:135], v[40:41]
	v_pk_mul_f32 v[30:31], v[140:141], v[30:31]
	v_pk_mul_f32 v[28:29], v[138:139], v[28:29]
	v_pk_mul_f32 v[34:35], v[144:145], v[34:35]
	v_pk_mul_f32 v[32:33], v[142:143], v[32:33]
	v_pk_mul_f32 v[22:23], v[148:149], v[22:23]
	v_pk_mul_f32 v[20:21], v[146:147], v[20:21]
	v_pk_mul_f32 v[26:27], v[152:153], v[26:27]
	v_pk_mul_f32 v[24:25], v[150:151], v[24:25]
	v_pk_mul_f32 v[18:19], v[156:157], v[18:19]
	v_pk_mul_f32 v[16:17], v[154:155], v[16:17]
	global_store_dwordx4 v[98:99], v[0:3], off
	global_store_dwordx4 v[98:99], v[4:7], off offset:16
	global_store_dwordx4 v[98:99], v[8:11], off offset:2048
	global_store_dwordx4 v[98:99], v[12:15], off offset:2064
	global_store_dwordx4 v[102:103], v[60:63], off offset:-4096
	global_store_dwordx4 v[104:105], v[52:55], off offset:16
	global_store_dwordx4 v[104:105], v[56:59], off offset:2048
	global_store_dwordx4 v[104:105], v[44:47], off offset:2064
	global_store_dwordx4 v[102:103], v[48:51], off
	global_store_dwordx4 v[102:103], v[36:39], off offset:16
	global_store_dwordx4 v[102:103], v[40:43], off offset:2048
	global_store_dwordx4 v[102:103], v[28:31], off offset:2064
	global_store_dwordx4 v[100:101], v[32:35], off
	global_store_dwordx4 v[100:101], v[20:23], off offset:16
	global_store_dwordx4 v[100:101], v[24:27], off offset:2048
	global_store_dwordx4 v[100:101], v[16:19], off offset:2064
	s_cbranch_scc1 .LBB0_842
